# v84 + even-B loop-invariant lane masks kept in s[98:101] for the phase (3 fewer v_readlane per iteration)
# baseline (speedup 1.0000x reference)
; #define LAS __attribute__((address_space(3)))
;     unsigned char* ws = p.ws;
;     unsigned* headP = (unsigned*)(ws + WS_CTL) + CW_QUEUE + 64 * qsel; unsigned* headS = headP + 32;
;     volatile LAS unsigned* slot = (volatile LAS unsigned*)(lds + LDSCTL_OFF + 128);
;     const bf16* QB = (const bf16*)(ws + WS_QB); const bf16* KB = (const bf16*)(ws + WS_KB); const bf16* VT = (const bf16*)(ws + WS_VT); const bf16* VS = (const bf16*)(ws + WS_VS); bf16* AO = (bf16*)(ws + WS_AO);
;     const float* ck = (const float*)p.in[I_CK]; const float* cv = (const float*)p.in[I_CV];
;     typedef const __attribute__((address_space(4))) int* cint_p;
;     constexpr unsigned N_ATT = NB_P * SBH * 16, N_FIX = NB_P * 64, N_PQ = N_ATT + N_FIX, N_SQ = 2 * NB_S;
;     constexpr int KLD = 72, VLD = 68, KBUF = 64 * KLD * 2, VBUF = 64 * VLD * 2;
;     LAS unsigned char* kl = lds; LAS unsigned char* vl = lds + 2 * KBUF;
;     LAS float* xo = (LAS float*)(lds + 36864); LAS float* xp = (LAS float*)(lds + 36864 + 32768);
;     int tid = tid_; asm volatile("" : "+v"(tid));
;     const int lane = tid & 63, r = lane & 31, h2 = lane >> 5;
;     bool pAct = false, pEmpty = (p.mode == 1); int pb = 0, ph = 0, Q0 = 0, kt = 0, cur = 0;
;     bf16x8 qf[4]; f32x16 accO[2]; float pcarry = 1.f, pbias2 = 0.f; u32x4 kr0, vr0, kr1, vr1;
;     const int srow = tid >> 3, sch = tid & 7, kdst = srow * (KLD * 2) + sch * 16, vdst = srow * (VLD * 2) + sch * 16;
;     const bf16* ksrc = KB; const bf16* vsrc = VT;
;     bool sAct = false, sEmpty = (p.mode == 2); int ss = 0, shalf = 0, st = 0;
;     const int hg = wave & 1, seg = wave >> 1, hh = lane >> 4, c = lane & 15, sh = 4 * hg + hh, qme = 2 * (c & 1) + ((c >> 1) & 1);
;     const float sbias2 = ((const float*)p.in[I_SBB])[sh] * LOG2E;
;     LAS f32x4* sq = (LAS f32x4*)(lds + 36864 + 40960) + wave * 256 + lane;
;     SmpAcc A; SmpKV R0, R1; cint_p spt = (cint_p)(unsigned long long)p.in[I_PT];
.LBB0_528:
	v_readlane_b32 s8, v244, 3
	s_cmp_lt_i32 s28, 6
	v_readlane_b32 s14, v244, 9
	s_cselect_b64 s[2:3], -1, 0
	v_readlane_b32 s15, v244, 10
	s_add_u32 s0, s14, 0x1a900000
	s_addc_u32 s1, s15, 0
	v_writelane_b32 v243, s0, 24
	v_readlane_b32 s9, v244, 4
	v_readlane_b32 s10, v244, 5
	v_writelane_b32 v243, s1, 25
	v_writelane_b32 v243, s2, 26
	s_and_b64 s[0:1], s[2:3], s[4:5]
	s_andn2_b64 vcc, exec, s[0:1]
	v_writelane_b32 v243, s3, 27
	s_mov_b64 s[0:1], s[28:29]
	s_mov_b32 s2, s30
	v_writelane_b32 v243, s0, 28
	v_readlane_b32 s11, v244, 6
	v_readlane_b32 s12, v244, 7
	v_writelane_b32 v243, s1, 29
	v_writelane_b32 v243, s2, 30
	v_readlane_b32 s13, v244, 8
	v_writelane_b32 v243, s3, 31
	s_cbranch_vccnz .LBB0_657
	v_readlane_b32 s8, v244, 3
	v_readlane_b32 s14, v244, 9
	v_readlane_b32 s15, v244, 10
	s_add_u32 s0, s14, 0x10080
	s_addc_u32 s1, s15, 0
	s_add_u32 s62, s14, 0x18700000
	s_addc_u32 s63, s15, 0
	s_waitcnt vmcnt(0)
	v_mov_b32_e32 v189, v0
	s_bfe_u32 s3, s33, 0x10006
	s_lshl_b32 s2, s3, 2
	v_bfe_u32 v1, v189, 4, 2
	v_or_b32_e32 v8, s2, v1
	v_bfrev_b32_e32 v2, v189
	v_readlane_b32 s36, v244, 43
	v_ashrrev_i32_e32 v4, 30, v2
	v_lshlrev_b32_e32 v2, 2, v8
	v_readlane_b32 s42, v244, 49
	v_readlane_b32 s43, v244, 50
	v_writelane_b32 v243, s97, 32
	v_writelane_b32 v243, s0, 33
	v_readlane_b32 s10, v244, 5
	v_readlane_b32 s11, v244, 6
	v_writelane_b32 v243, s1, 34
	global_load_dword v2, v2, s[42:43]
	s_lshl_b32 s0, s90, 12
	s_add_i32 s0, s0, 0
	v_writelane_b32 v243, s0, 35
	s_add_i32 s0, s0, 0x13000
	s_add_u32 s70, s14, 0x10000
	s_addc_u32 s71, s15, 0
	s_add_u32 s10, s14, 0x19800000
	s_addc_u32 s11, s15, 0
	s_cmp_eq_u32 s30, 2
	v_ashrrev_i32_e32 v184, 3, v189
	v_and_b32_e32 v5, 7, v189
	s_movk_i32 s1, 0x90
	s_cselect_b64 s[4:5], -1, 0
	s_add_u32 s76, s14, 0x17600000
	v_lshlrev_b32_e32 v6, 4, v5
	v_mul_lo_u32 v7, v184, s1
	s_addc_u32 s77, s15, 0
	v_writelane_b32 v243, s4, 36
	s_cmp_eq_u32 s30, 1
	v_add3_u32 v201, 0, v7, v6
	v_writelane_b32 v243, s5, 37
	s_cselect_b64 s[56:57], -1, 0
	s_lshl_b32 s36, s90, 5
	s_and_b32 s4, s90, 0x3fffffe
	v_lshlrev_b32_e32 v190, 3, v5
	v_lshlrev_b32_e32 v5, 2, v189
	s_sub_u32 s4, 0, s4
	v_and_b32_e32 v198, 60, v5
	s_subb_u32 s5, 0, 0
	v_lshlrev_b32_e32 v196, 6, v8
	v_writelane_b32 v243, s4, 38
	v_lshlrev_b32_e32 v10, 1, v198
	v_and_b32_e32 v5, 1, v189
	v_writelane_b32 v243, s5, 39
	s_mov_b64 s[4:5], 0x1a800000
	v_readlane_b32 s9, v244, 4
	v_writelane_b32 v243, s33, 40
	v_and_b32_e32 v187, 63, v189
	v_lshlrev_b32_e32 v188, 2, v187
	s_cmpk_lt_u32 s33, 0x80
	v_lshlrev_b32_e32 v195, 4, v187
	v_lshl_or_b32 v200, s3, 8, v188
	s_cselect_b64 s[16:17], -1, 0
	s_add_i32 s3, 0, 0x11000
	v_add_u32_e32 v222, s3, v195
	v_and_b32_e32 v3, 3, v189
	v_readlane_b32 s12, v244, 7
	v_readlane_b32 s13, v244, 8
	v_bfe_u32 v12, v189, 5, 1
	v_and_b32_e32 v191, 31, v189
	v_readlane_b32 s37, v244, 44
	v_readlane_b32 s38, v244, 45
	v_readlane_b32 s39, v244, 46
	v_readlane_b32 s40, v244, 47
	v_readlane_b32 s41, v244, 48
	v_readlane_b32 s44, v244, 51
	v_readlane_b32 s45, v244, 52
	v_readlane_b32 s46, v244, 53
	v_readlane_b32 s47, v244, 54
	v_readlane_b32 s48, v244, 55
	v_readlane_b32 s49, v244, 56
	v_readlane_b32 s50, v244, 57
	v_readlane_b32 s51, v244, 58
	v_lshlrev_b32_e32 v186, 3, v12
	v_lshl_add_u32 v218, v12, 4, 0
	v_mov_b32_e32 v214, 1.0
	v_mbcnt_lo_u32_b32 v38, -1, 0
	s_mov_b32 s65, 0
	s_mov_b64 s[66:67], 0x10000
	v_add_u32_e32 v197, s0, v195
	v_cmp_eq_u32_e64 s[0:1], 0, v189
	v_ashrrev_i32_e32 v185, 31, v184
	s_mov_b64 s[6:7], 0
	v_mul_u32_u24_e32 v219, 0x90, v191
	v_lshlrev_b32_e32 v206, 2, v12
	v_sub_u32_e32 v220, v218, v186
	v_mul_u32_u24_e32 v221, 0x88, v191
	v_mov_b64_e32 v[210:211], s[10:11]
	v_mov_b64_e32 v[208:209], s[62:63]
	s_waitcnt vmcnt(0)
; #define LAS __attribute__((address_space(3)))
;     ...
;     int tid = tid_; asm volatile("" : "+v"(tid));
;     const int lane = tid & 63, r = lane & 31, h2 = lane >> 5;
;     bool pAct = false, pEmpty = (p.mode == 1); int pb = 0, ph = 0, Q0 = 0, kt = 0, cur = 0;
;     bf16x8 qf[4]; f32x16 accO[2]; float pcarry = 1.f, pbias2 = 0.f; u32x4 kr0, vr0, kr1, vr1;
;     const int srow = tid >> 3, sch = tid & 7, kdst = srow * (KLD * 2) + sch * 16, vdst = srow * (VLD * 2) + sch * 16;
;     const bf16* ksrc = KB; const bf16* vsrc = VT;
;     bool sAct = false, sEmpty = (p.mode == 2); int ss = 0, shalf = 0, st = 0;
;     const int hg = wave & 1, seg = wave >> 1, hh = lane >> 4, c = lane & 15, sh = 4 * hg + hh, qme = 2 * (c & 1) + ((c >> 1) & 1);
;     const float sbias2 = ((const float*)p.in[I_SBB])[sh] * LOG2E;
;     LAS f32x4* sq = (LAS f32x4*)(lds + 36864 + 40960) + wave * 256 + lane;
;     SmpAcc A; SmpKV R0, R1; cint_p spt = (cint_p)(unsigned long long)p.in[I_PT];
; #pragma unroll
;     for (int i = 0; i < 4; ++i) { qf[i] = (bf16x8){0, 0, 0, 0, 0, 0, 0, 0}; A.acc[i] = (f32x4){0.f, 0.f, 0.f, 0.f}; }
;     A.carry = 1.f;
; #pragma unroll
;     for (int i = 0; i < 16; ++i) { accO[0][i] = 0.f; accO[1][i] = 0.f; }
;     kr0 = (u32x4){0u, 0u, 0u, 0u}; vr0 = kr0; kr1 = kr0; vr1 = kr0;
; #pragma unroll
;     for (int u = 0; u < 4; ++u) { R0.k[u] = (f32x4){0.f, 0.f, 0.f, 0.f}; R0.v[u] = R0.k[u]; R1.k[u] = R0.k[u]; R1.v[u] = R0.k[u]; }
	v_mul_f32_e32 v199, 0x3fb8aa3b, v2
	v_and_b32_e32 v2, -8, v189
	v_sub_u32_e32 v207, v201, v2
	v_mov_b32_e32 v2, 0
	v_mov_b32_e32 v7, v2
	v_lshl_add_u64 v[192:193], s[10:11], 0, v[6:7]
	v_lshlrev_b32_e32 v6, 7, v8
	v_lshl_add_u64 v[8:9], s[62:63], 0, v[6:7]
	v_mov_b32_e32 v11, v2
	v_lshl_add_u64 v[6:7], s[14:15], 0, v[6:7]
	v_lshl_add_u64 v[6:7], v[6:7], 0, v[10:11]
	v_lshl_add_u64 v[204:205], v[6:7], 0, s[4:5]
	v_cmp_eq_u32_e64 s[4:5], 0, v5
	v_and_b32_e32 v5, 2, v189
	v_cmp_eq_u32_e64 s[8:9], 0, v5
	v_mov_b32_e32 v5, v2
	v_mov_b32_e32 v74, v2
	v_writelane_b32 v243, s8, 41
	v_mov_b32_e32 v75, v2
	v_mov_b32_e32 v90, v2
	v_writelane_b32 v243, s9, 42
	v_cmp_gt_u32_e64 s[8:9], 32, v187
	v_mov_b32_e32 v91, v2
	v_mov_b32_e32 v72, v2
	v_writelane_b32 v243, s8, 43
	v_mov_b32_e32 v73, v2
	v_mov_b32_e32 v88, v2
	v_writelane_b32 v243, s9, 44
	s_lshl_b32 s8, s90, 10
	v_writelane_b32 v243, s8, 45
	s_add_i32 s8, s3, s8
	s_or_b32 s3, s90, 6
	v_writelane_b32 v243, s8, 46
	s_lshl_b32 s8, s3, 10
	s_lshl_b32 s3, s3, 12
	v_writelane_b32 v243, s8, 47
	s_add_i32 s3, s3, 0
	v_writelane_b32 v243, s3, 48
	s_or_b32 s3, s90, 4
	s_lshl_b32 s8, s3, 10
	s_lshl_b32 s3, s3, 12
	v_writelane_b32 v243, s8, 49
	s_add_i32 s3, s3, 0
	v_writelane_b32 v243, s3, 50
	s_mov_b32 s8, s90
	v_writelane_b32 v243, s8, 51
	s_or_b32 s3, s90, 2
	v_mov_b32_e32 v89, v2
	v_writelane_b32 v243, s9, 52
	s_lshl_b32 s8, s3, 10
	s_lshl_b32 s3, s3, 12
	v_writelane_b32 v243, s8, 53
	s_add_i32 s3, s3, 0
	v_writelane_b32 v243, s3, 54
	v_cmp_eq_u32_e64 s[8:9], 0, v187
	s_add_u32 s34, s14, 0x1ea00000
	s_addc_u32 s35, s15, 0
	v_writelane_b32 v243, s8, 55
	s_add_u32 s96, s12, 0x8206000
	s_addc_u32 s97, s13, 0
	v_writelane_b32 v243, s9, 56
	v_cmp_eq_u16_e64 s[8:9], 3, v3
	s_add_u32 s3, s14, 0x29c00000
	v_mov_b64_e32 v[142:143], v[90:91]
	v_writelane_b32 v243, s8, 57
	v_mov_b64_e32 v[126:127], v[90:91]
	v_mov_b64_e32 v[110:111], v[90:91]
	v_writelane_b32 v243, s9, 58
	v_cmp_gt_i16_e64 s[8:9], 0, v4
	v_mov_b32_e32 v4, v2
	v_mov_b64_e32 v[98:99], v[90:91]
	v_writelane_b32 v243, s8, 59
	v_mov_b64_e32 v[150:151], v[90:91]
	v_mov_b64_e32 v[134:135], v[90:91]
	v_writelane_b32 v243, s9, 60
	v_cmp_eq_u16_e64 s[8:9], 0, v3
	v_mov_b32_e32 v3, v2
	v_mov_b64_e32 v[118:119], v[90:91]
	v_writelane_b32 v243, s8, 61
	v_mov_b64_e32 v[102:103], v[90:91]
	v_mov_b64_e32 v[114:115], v[90:91]
	v_writelane_b32 v243, s9, 62
	v_writelane_b32 v243, s3, 63
	s_addc_u32 s3, s15, 0
	s_add_u32 s2, s14, s2
	v_writelane_b32 v242, s3, 0
	s_addc_u32 s3, s15, 0
	s_add_u32 s2, s2, 0x20000
	v_writelane_b32 v242, s2, 1
	s_addc_u32 s2, s3, 0
	v_writelane_b32 v242, s2, 2
	v_writelane_b32 v242, s16, 3
	s_xor_b64 s[12:13], s[16:17], -1
	s_mov_b32 s2, 0
	v_writelane_b32 v242, s17, 4
	v_writelane_b32 v242, s12, 5
	v_mov_b64_e32 v[130:131], v[90:91]
	v_mov_b64_e32 v[146:147], v[90:91]
	v_writelane_b32 v242, s13, 6
	v_readlane_b32 s12, v244, 27
	v_readlane_b32 s13, v244, 28
	v_mov_b64_e32 v[94:95], v[90:91]
	v_writelane_b32 v242, s12, 7
	v_mov_b64_e32 v[106:107], v[90:91]
	v_mov_b64_e32 v[122:123], v[90:91]
	v_writelane_b32 v242, s13, 8
	v_writelane_b32 v242, s2, 9
	v_writelane_b32 v242, s2, 10
	v_mov_b64_e32 v[138:139], v[90:91]
	v_mov_b64_e32 v[154:155], v[90:91]
	v_mov_b64_e32 v[158:159], v[90:91]
	v_mov_b64_e32 v[162:163], v[90:91]
	v_mov_b64_e32 v[166:167], v[90:91]
	v_mov_b64_e32 v[86:87], v[74:75]
	v_mov_b64_e32 v[82:83], v[74:75]
	v_mov_b64_e32 v[78:79], v[74:75]
	v_writelane_b32 v242, s2, 11
	v_mov_b64_e32 v[174:175], v[4:5]
	v_mov_b64_e32 v[170:171], v[4:5]
	v_lshl_add_u64 v[202:203], v[8:9], 0, v[10:11]
	v_mov_b32_e32 v6, v2
	v_mov_b32_e32 v7, v2
	v_mov_b32_e32 v8, v2
	v_mov_b32_e32 v9, v2
	v_mov_b32_e32 v10, v2
	v_mov_b32_e32 v12, v2
	v_mov_b32_e32 v13, v2
	v_mov_b32_e32 v14, v2
	v_mov_b32_e32 v15, v2
	v_mov_b32_e32 v16, v2
	v_mov_b32_e32 v17, v2
	v_mov_b32_e32 v18, v2
	v_mov_b32_e32 v19, v2
	v_mov_b32_e32 v20, v2
	v_mov_b32_e32 v21, v2
	v_mov_b32_e32 v22, v2
	v_mov_b32_e32 v23, v2
	v_mov_b32_e32 v24, v2
	v_mov_b32_e32 v25, v2
	v_mov_b32_e32 v26, v2
	v_mov_b32_e32 v27, v2
	v_mov_b32_e32 v28, v2
	v_mov_b32_e32 v29, v2
	v_mov_b32_e32 v30, v2
	v_mov_b32_e32 v31, v2
	v_mov_b32_e32 v32, v2
	v_mov_b32_e32 v33, v2
	v_mov_b32_e32 v34, v2
	v_mov_b32_e32 v35, v2
	v_mov_b32_e32 v36, v2
	v_mov_b32_e32 v37, v2
	s_add_i32 s51, 0, 0x20080
	s_mov_b32 s45, 0x1a900000
	s_mov_b32 s46, 0xe902000
	s_mov_b32 s33, 0xe903000
	s_mov_b32 s68, 0xe904000
	s_mov_b32 s49, 0x1ca01000
	s_mov_b32 s50, 0x1da01000
	s_mov_b32 s39, 0xe906000
	s_mov_b32 s40, 0xe907000
	s_mov_b32 s41, 0xe908000
	s_mov_b32 s42, 0xe909000
	s_mov_b32 s43, 0x1ca02000
	s_mov_b32 s44, 0x1da02000
	s_mov_b32 s37, 0xe90b000
	s_mov_b32 s47, 0xe90c000
	s_mov_b32 s48, 0xe90d000
	s_mov_b32 s38, 0xe90e000
	s_mov_b32 s3, 0x1ca03000
	s_mov_b32 s10, 0x1da03000
	s_mov_b32 s11, 0xe910000
	s_mov_b32 s78, 0xe911000
	s_mov_b32 s79, 0xe912000
	s_mov_b32 s54, 0xe913000
	s_mov_b32 s55, 0x1a901000
	s_mov_b32 s52, 0x1a902000
	s_mov_b32 s53, 0x1a903000
	s_mov_b32 s58, 0x1a904000
	s_mov_b32 s59, 0x1a905000
	s_mov_b32 s8, 0x1a906000
	s_mov_b32 s9, 0x1a907000
	v_mbcnt_hi_u32_b32 v223, -1, v38
	v_xor_b32_e32 v254, 32, v223
	v_lshlrev_b32_e32 v254, 2, v254
	v_readlane_b32 s98, v243, 41
	v_readlane_b32 s99, v243, 42
	v_readlane_b32 s100, v243, 43
	v_readlane_b32 s101, v243, 44
	v_mov_b64_e32 v[140:141], v[88:89]
	v_mov_b64_e32 v[124:125], v[88:89]
	v_mov_b64_e32 v[108:109], v[88:89]
	v_mov_b64_e32 v[96:97], v[88:89]
	v_mov_b64_e32 v[148:149], v[88:89]
	v_mov_b64_e32 v[132:133], v[88:89]
	v_mov_b64_e32 v[116:117], v[88:89]
	v_mov_b64_e32 v[100:101], v[88:89]
	v_mov_b64_e32 v[112:113], v[88:89]
	v_mov_b64_e32 v[128:129], v[88:89]
	v_mov_b64_e32 v[144:145], v[88:89]
	v_mov_b64_e32 v[92:93], v[88:89]
	v_mov_b64_e32 v[104:105], v[88:89]
	v_mov_b64_e32 v[120:121], v[88:89]
	v_mov_b64_e32 v[136:137], v[88:89]
	v_mov_b64_e32 v[152:153], v[88:89]
	v_mov_b64_e32 v[156:157], v[88:89]
	v_mov_b64_e32 v[160:161], v[88:89]
	v_mov_b64_e32 v[164:165], v[88:89]
	v_mov_b64_e32 v[84:85], v[72:73]
	v_mov_b64_e32 v[80:81], v[72:73]
	v_mov_b64_e32 v[76:77], v[72:73]
	v_mov_b32_e32 v213, v214
	v_mov_b64_e32 v[172:173], v[2:3]
	v_mov_b64_e32 v[168:169], v[2:3]
	v_mov_b32_e32 v38, 0
	s_mov_b32 s75, 0
	s_mov_b32 s74, 0
	s_mov_b32 s73, 0
	s_mov_b32 s72, 0
	s_mov_b64 s[60:61], 0
	v_writelane_b32 v242, s96, 12
	v_readlane_b32 s14, v244, 29
	v_readlane_b32 s15, v244, 30
	v_readlane_b32 s16, v244, 31
	v_readlane_b32 s17, v244, 32
	v_readlane_b32 s18, v244, 33
	v_readlane_b32 s19, v244, 34
	v_readlane_b32 s20, v244, 35
	v_readlane_b32 s21, v244, 36
	v_readlane_b32 s22, v244, 37
	v_readlane_b32 s23, v244, 38
	v_readlane_b32 s24, v244, 39
	v_readlane_b32 s25, v244, 40
	v_readlane_b32 s26, v244, 41
	v_readlane_b32 s27, v244, 42
	v_writelane_b32 v242, s97, 13
	s_branch .LBB0_533

; #define LAS __attribute__((address_space(3)))
; DI unsigned pk2(float lo, float hi) { f32x2 v = {lo, hi}; return __builtin_bit_cast(unsigned, __builtin_convertvector(v, bf16v2)); }
; #define MFMA32(a, b, c) __builtin_amdgcn_mfma_f32_32x32x16_bf16((a), (b), (c), 0, 0, 0)
; DI void prompt_tile(const LAS unsigned char* kc, const LAS unsigned char* vc, const bf16x8 (&qf)[4], f32x16 (&accO)[2], float& carry, float bias2, int key0, int Q0, int r, int h2) {
;     ...
;         float R[2][4], Rp[2][4];
; #pragma unroll
;         for (int kb = 0; kb < 2; ++kb)
; #pragma unroll
;             for (int q = 0; q < 4; ++q) { const f32x2 pr = kp[kb][2 * q] * kp[kb][2 * q + 1]; R[kb][q] = pr.x * pr.y; Rp[kb][q] = __shfl_xor(R[kb][q], 32); }
;         float c = carry;
; #pragma unroll
;     ...
; #pragma unroll
;             for (int q = 3; q >= 0; --q) {
;                 const float E3 = c * (h2 ? 1.0f : Rp[kb][q]);
;                 c *= R[kb][q] * Rp[kb][q];
;                 const f32x2 ka = kp[kb][2 * q], kc = kp[kb][2 * q + 1];
;                 const float E2 = E3 * kc.y, E1 = E2 * kc.x, E0 = E1 * ka.y;
;                 const f32x2 w01 = (1.0f - ka) * (f32x2){E0, E1}, w23 = (1.0f - kc) * (f32x2){E2, E3};
;                 sk[kb][4 * q] = w01.x; sk[kb][4 * q + 1] = w01.y; sk[kb][4 * q + 2] = w23.x; sk[kb][4 * q + 3] = w23.y;
;             }
;         carry = c;
; #pragma unroll
;         for (int kb = 0; kb < 2; ++kb)
; #pragma unroll
;             for (int s = 0; s < 2; ++s) {
;                 u32x4 wp;
; #pragma unroll
;                 for (int j = 0; j < 4; ++j) wp[j] = pk2(sk[kb][8 * s + 2 * j], sk[kb][8 * s + 2 * j + 1]);
;                 const bf16x8 wf = __builtin_bit_cast(bf16x8, wp);
; #pragma unroll
;                 for (int db = 0; db < 2; ++db) {
;                     const LAS unsigned char* va = vc + (32 * db + r) * (VLD * 2) + (32 * kb + 16 * s + 4 * h2) * 2;
;                     const u32x2 lo = *(const LAS u32x2*)va, hi = *(const LAS u32x2*)(va + 16);
;                     const bf16x8 vf = __builtin_bit_cast(bf16x8, (u32x4){lo.x, lo.y, hi.x, hi.y});
;                     accO[db] = MFMA32(vf, wf, accO[db]);
;                 }
;             }
.LBB0_573:
	v_pk_mul_f32 v[52:53], v[216:217], v[62:63]
	v_pk_mul_f32 v[224:225], v[52:53], v[52:53] op_sel:[0,1] op_sel_hi:[1,0]
	v_pk_mul_f32 v[52:53], v[64:65], v[66:67]
	v_pk_mul_f32 v[228:229], v[52:53], v[52:53] op_sel:[0,1] op_sel_hi:[1,0]
	v_pk_mul_f32 v[52:53], v[48:49], v[50:51]
	v_pk_mul_f32 v[52:53], v[52:53], v[52:53] op_sel:[0,1] op_sel_hi:[1,0]
	ds_bpermute_b32 v53, v254, v52
	v_pk_mul_f32 v[234:235], v[44:45], v[46:47]
	v_mov_b32_e32 v240, v234
	v_mov_b32_e32 v241, v52
	v_mov_b32_e32 v52, v235
	v_pk_mul_f32 v[232:233], v[68:69], v[70:71]
	s_waitcnt lgkmcnt(0)
	v_cndmask_b32_e64 v39, 1.0, v53, s[100:101]
	v_pk_mul_f32 v[52:53], v[240:241], v[52:53]
	v_pk_mul_f32 v[232:233], v[232:233], v[232:233] op_sel:[0,1] op_sel_hi:[1,0]
	ds_bpermute_b32 v212, v254, v52
	ds_bpermute_b32 v233, v254, v232
	v_mul_f32_e32 v237, v213, v39
	v_pk_mul_f32 v[230:231], v[40:41], v[42:43]
	v_mul_f32_e32 v236, v51, v237
	s_waitcnt lgkmcnt(1)
	v_pk_mul_f32 v[52:53], v[52:53], v[212:213]
	v_mul_f32_e32 v239, v50, v236
	v_pk_add_f32 v[50:51], v[50:51], 1.0 op_sel_hi:[1,0] neg_lo:[1,0] neg_hi:[1,0]
	v_pk_mul_f32 v[234:235], v[52:53], v[52:53] op_sel:[0,1] op_sel_hi:[1,0]
	s_waitcnt lgkmcnt(0)
	v_cndmask_b32_e64 v39, 1.0, v233, s[100:101]
	v_mov_b32_e32 v240, v230
	v_mov_b32_e32 v241, v232
	v_mov_b32_e32 v232, v231
	v_pk_mul_f32 v[50:51], v[50:51], v[236:237]
	v_mul_f32_e32 v237, v39, v234
	v_pk_mul_f32 v[230:231], v[240:241], v[232:233]
	ds_bpermute_b32 v229, v254, v228
	v_mul_f32_e32 v238, v49, v239
	v_pk_add_f32 v[48:49], v[48:49], 1.0 op_sel_hi:[1,0] neg_lo:[1,0] neg_hi:[1,0]
	v_mul_f32_e32 v236, v71, v237
	ds_bpermute_b32 v232, v254, v230
	v_pk_mul_f32 v[48:49], v[48:49], v[238:239]
	v_mul_f32_e32 v239, v70, v236
	v_mul_f32_e32 v238, v69, v239
	v_pk_add_f32 v[68:69], v[68:69], 1.0 op_sel_hi:[1,0] neg_lo:[1,0] neg_hi:[1,0]
	v_pk_mul_f32 v[226:227], v[58:59], v[60:61]
	v_pk_mul_f32 v[238:239], v[68:69], v[238:239]
	v_pk_add_f32 v[68:69], v[70:71], 1.0 op_sel_hi:[1,0] neg_lo:[1,0] neg_hi:[1,0]
	v_mov_b32_e32 v233, v234
	v_pk_mul_f32 v[70:71], v[68:69], v[236:237]
	v_mov_b32_e32 v236, v226
	v_mov_b32_e32 v237, v228
	v_mov_b32_e32 v228, v227
	s_waitcnt lgkmcnt(0)
	v_pk_mul_f32 v[230:231], v[230:231], v[232:233]
	v_pk_mul_f32 v[226:227], v[236:237], v[228:229]
	v_pk_mul_f32 v[68:69], v[230:231], v[230:231] op_sel:[0,1] op_sel_hi:[1,0]
	v_cndmask_b32_e64 v52, 1.0, v229, s[100:101]
	ds_bpermute_b32 v228, v254, v226
	ds_bpermute_b32 v225, v254, v224
	v_mul_f32_e32 v233, v52, v68
	v_cndmask_b32_e64 v39, 1.0, v232, s[100:101]
	v_mul_f32_e32 v232, v67, v233
	v_mul_f32_e32 v235, v66, v232
	v_pk_mul_f32 v[54:55], v[56:57], v[4:5]
	v_mul_f32_e32 v234, v65, v235
	v_pk_add_f32 v[64:65], v[64:65], 1.0 op_sel_hi:[1,0] neg_lo:[1,0] neg_hi:[1,0]
	v_mov_b32_e32 v229, v68
	v_pk_mul_f32 v[234:235], v[64:65], v[234:235]
	v_pk_add_f32 v[64:65], v[66:67], 1.0 op_sel_hi:[1,0] neg_lo:[1,0] neg_hi:[1,0]
	s_waitcnt lgkmcnt(1)
	v_cndmask_b32_e64 v52, 1.0, v228, s[100:101]
	v_pk_mul_f32 v[226:227], v[226:227], v[228:229]
	v_mov_b32_e32 v228, v54
	v_mov_b32_e32 v229, v224
	v_mov_b32_e32 v224, v55
	v_pk_mul_f32 v[232:233], v[64:65], v[232:233]
	v_pk_mul_f32 v[64:65], v[226:227], v[226:227] op_sel:[0,1] op_sel_hi:[1,0]
	s_waitcnt lgkmcnt(0)
	v_pk_mul_f32 v[54:55], v[228:229], v[224:225]
	v_cndmask_b32_e64 v65, 1.0, v225, s[100:101]
	ds_bpermute_b32 v224, v254, v54
	v_mul_f32_e32 v67, v65, v64
	v_mul_f32_e32 v66, v63, v67
	v_mul_f32_e32 v69, v62, v66
	v_mul_f32_e32 v68, v217, v69
	v_pk_add_f32 v[216:217], v[216:217], 1.0 op_sel_hi:[1,0] neg_lo:[1,0] neg_hi:[1,0]
	v_mov_b32_e32 v225, v64
	v_pk_mul_f32 v[68:69], v[216:217], v[68:69]
	v_pk_add_f32 v[62:63], v[62:63], 1.0 op_sel_hi:[1,0] neg_lo:[1,0] neg_hi:[1,0]
	s_waitcnt lgkmcnt(0)
	v_cndmask_b32_e64 v3, 1.0, v224, s[100:101]
	v_pk_mul_f32 v[216:217], v[54:55], v[224:225]
	v_pk_mul_f32 v[66:67], v[62:63], v[66:67]
	v_mul_f32_e32 v63, v3, v217
	s_mul_i32 s12, s2, 0x2200
	v_mul_f32_e32 v62, v5, v63
	v_mul_f32_e32 v55, v4, v62
	v_add3_u32 v3, v220, s12, v221
	v_mul_f32_e32 v54, v57, v55
	v_pk_add_f32 v[56:57], v[56:57], 1.0 op_sel_hi:[1,0] neg_lo:[1,0] neg_hi:[1,0]
	v_add_u32_e32 v213, 0x4800, v3
	v_pk_mul_f32 v[64:65], v[56:57], v[54:55]
	ds_read2_b64 v[54:57], v213 offset1:2
	v_pk_add_f32 v[4:5], v[4:5], 1.0 op_sel_hi:[1,0] neg_lo:[1,0] neg_hi:[1,0]
	v_add_u32_e32 v3, 0x5800, v3
	v_pk_mul_f32 v[4:5], v[4:5], v[62:63]
	v_cvt_pk_bf16_f32 v62, v64, v65
	v_cvt_pk_bf16_f32 v64, v68, v69
	v_cvt_pk_bf16_f32 v65, v66, v67
	ds_read2_b64 v[66:69], v3 offset0:32 offset1:34
	v_cvt_pk_bf16_f32 v63, v4, v5
	v_mul_f32_e32 v5, v52, v227
	v_mul_f32_e32 v4, v61, v5
	s_waitcnt lgkmcnt(1)
	v_mfma_f32_32x32x16_bf16 v[6:21], v[54:57], v[62:65], v[6:21]
	v_mul_f32_e32 v55, v60, v4
	v_mul_f32_e32 v54, v59, v55
	v_add_f32_e64 v56, -v58, 1.0
	v_add_f32_e64 v57, -v59, 1.0
	v_add_f32_e64 v60, -v60, 1.0
	v_add_f32_e64 v61, -v61, 1.0
	v_pk_mul_f32 v[58:59], v[56:57], v[54:55]
	ds_read2_b64 v[54:57], v213 offset0:4 offset1:6
	v_pk_mul_f32 v[4:5], v[60:61], v[4:5]
	s_waitcnt lgkmcnt(1)
	v_mfma_f32_32x32x16_bf16 v[22:37], v[66:69], v[62:65], v[22:37]
	ds_read2_b64 v[62:65], v3 offset0:36 offset1:38
	v_cvt_pk_bf16_f32 v58, v58, v59
	v_cvt_pk_bf16_f32 v59, v4, v5
	v_mul_f32_e32 v5, v39, v231
	v_cvt_pk_bf16_f32 v60, v234, v235
	v_cvt_pk_bf16_f32 v61, v232, v233
	v_mul_f32_e32 v4, v43, v5
	s_waitcnt lgkmcnt(1)
	v_mfma_f32_32x32x16_bf16 v[6:21], v[54:57], v[58:61], v[6:21]
	v_mul_f32_e32 v55, v42, v4
	v_mul_f32_e32 v54, v41, v55
	v_add_f32_e64 v40, -v40, 1.0
	v_add_f32_e64 v41, -v41, 1.0
	v_add_f32_e64 v42, -v42, 1.0
	v_add_f32_e64 v43, -v43, 1.0
	v_pk_mul_f32 v[40:41], v[40:41], v[54:55]
	ds_read2_b64 v[54:57], v213 offset0:8 offset1:10
	v_pk_mul_f32 v[4:5], v[42:43], v[4:5]
	s_waitcnt lgkmcnt(1)
	v_mfma_f32_32x32x16_bf16 v[22:37], v[62:65], v[58:61], v[22:37]
	ds_read2_b64 v[58:61], v3 offset0:40 offset1:42
	v_cvt_pk_bf16_f32 v40, v40, v41
	v_cvt_pk_bf16_f32 v41, v4, v5
	v_cndmask_b32_e64 v4, 1.0, v212, s[100:101]
	v_mul_f32_e32 v5, v4, v53
	v_cvt_pk_bf16_f32 v42, v238, v239
	v_cvt_pk_bf16_f32 v43, v70, v71
	v_mul_f32_e32 v4, v47, v5
	s_waitcnt lgkmcnt(1)
	v_mfma_f32_32x32x16_bf16 v[6:21], v[54:57], v[40:43], v[6:21]
	v_mul_f32_e32 v57, v46, v4
	v_mul_f32_e32 v56, v45, v57
	v_add_f32_e64 v44, -v44, 1.0
	v_add_f32_e64 v45, -v45, 1.0
	ds_read2_b64 v[52:55], v213 offset0:12 offset1:14
	v_mul_f32_e32 v213, v216, v217
	s_waitcnt lgkmcnt(1)
	v_mfma_f32_32x32x16_bf16 v[22:37], v[58:61], v[40:43], v[22:37]
	v_mul_f32_e64 v40, v44, v56
	v_mul_f32_e64 v41, v45, v57
	v_add_f32_e64 v42, -v46, 1.0
	v_add_f32_e64 v43, -v47, 1.0
	ds_read2_b64 v[44:47], v3 offset0:44 offset1:46
	v_pk_mul_f32 v[4:5], v[42:43], v[4:5]
	v_cvt_pk_bf16_f32 v40, v40, v41
	v_cvt_pk_bf16_f32 v41, v4, v5
	v_cvt_pk_bf16_f32 v42, v48, v49
	v_cvt_pk_bf16_f32 v43, v50, v51
	s_waitcnt lgkmcnt(1)
	s_nop 0
	v_mfma_f32_32x32x16_bf16 v[6:21], v[52:55], v[40:43], v[6:21]
	s_waitcnt lgkmcnt(0)
	v_mfma_f32_32x32x16_bf16 v[22:37], v[44:47], v[40:43], v[22:37]

; DI float fexp2(float x) { return __builtin_amdgcn_exp2f(x); }
; DI float frcp(float x) { return __builtin_amdgcn_rcpf(x); }
; template <int CTRL> DI float dppf(float x) { return __builtin_bit_cast(float, __builtin_amdgcn_mov_dpp(__builtin_bit_cast(int, x), CTRL, 0xf, 0xf, true)); }
; DI void smp_key(SmpAcc& A, const f32x4 (&q)[4], const f32x4 K4, const f32x4 V4, float bias2, int c, bool masked) {
;     const f32x2 Kl = __builtin_shufflevector(K4, K4, 0, 1), Kh = __builtin_shufflevector(K4, K4, 2, 3);
;     f32x2 t0 = Kl * __builtin_shufflevector(q[0], q[0], 0, 1), t1 = Kl * __builtin_shufflevector(q[1], q[1], 0, 1), t2 = Kl * __builtin_shufflevector(q[2], q[2], 0, 1), t3 = Kl * __builtin_shufflevector(q[3], q[3], 0, 1);
;     t0 = __builtin_elementwise_fma(Kh, __builtin_shufflevector(q[0], q[0], 2, 3), t0); t1 = __builtin_elementwise_fma(Kh, __builtin_shufflevector(q[1], q[1], 2, 3), t1);
;     t2 = __builtin_elementwise_fma(Kh, __builtin_shufflevector(q[2], q[2], 2, 3), t2); t3 = __builtin_elementwise_fma(Kh, __builtin_shufflevector(q[3], q[3], 2, 3), t3);
;     const float z0 = t0.x + t0.y, z1 = t1.x + t1.y, z2 = t2.x + t2.y, z3 = t3.x + t3.y;
;     const bool b0 = c & 1, b1 = c & 2;
;     const float y0 = (b0 ? z2 : z0) + dppf<0xB1>(b0 ? z0 : z2), y1 = (b0 ? z3 : z1) + dppf<0xB1>(b0 ? z1 : z3);
;     float x = (b1 ? y1 : y0) + dppf<0x4E>(b1 ? y0 : y1);
;     x += dppf<0x124>(x); x += dppf<0x128>(x);
;     const float zz = fminf(x + bias2, 80.f), e = fexp2(zz); float kp = frcp(1.0f + e), sg = e * kp;
;     if (masked) { kp = 1.f; sg = 0.f; }
;     const float w = sg * A.carry;
;     A.carry *= kp;
;     const float w0 = dppf<0x00>(w), w1 = dppf<0xAA>(w), w2 = dppf<0x55>(w), w3 = dppf<0xFF>(w);
;     A.acc[0] += V4 * w0; A.acc[1] += V4 * w1; A.acc[2] += V4 * w2; A.acc[3] += V4 * w3;
.LBB0_576:
	v_cndmask_b32_e64 v3, 0, 1, s[6:7]
	v_cmp_ne_u32_e64 s[20:21], 1, v3
	s_andn2_b64 vcc, exec, s[6:7]
	s_cbranch_vccnz .LBB0_578
	ds_read_b128 v[40:43], v197
	ds_read_b128 v[44:47], v197 offset:1024
	ds_read_b128 v[48:51], v197 offset:2048
	ds_read_b128 v[52:55], v197 offset:3072
	s_waitcnt vmcnt(4) lgkmcnt(3)
	v_pk_mul_f32 v[4:5], v[144:145], v[40:41]
	s_waitcnt lgkmcnt(2)
	v_pk_mul_f32 v[56:57], v[144:145], v[44:45]
	s_waitcnt lgkmcnt(1)
	v_pk_mul_f32 v[58:59], v[144:145], v[48:49]
	s_waitcnt lgkmcnt(0)
	v_pk_mul_f32 v[60:61], v[144:145], v[52:53]
	v_pk_fma_f32 v[4:5], v[146:147], v[42:43], v[4:5]
	v_pk_fma_f32 v[56:57], v[146:147], v[46:47], v[56:57]
	v_pk_fma_f32 v[58:59], v[146:147], v[50:51], v[58:59]
	v_pk_fma_f32 v[60:61], v[146:147], v[54:55], v[60:61]
	v_add_f32_e32 v3, v4, v5
	v_add_f32_e32 v4, v56, v57
	v_add_f32_e32 v5, v58, v59
	v_add_f32_e32 v39, v60, v61
	v_cndmask_b32_e64 v56, v5, v3, s[4:5]
	v_cndmask_b32_e64 v3, v3, v5, s[4:5]
	v_cndmask_b32_e64 v5, v39, v4, s[4:5]
	v_cndmask_b32_e64 v4, v4, v39, s[4:5]
	v_add_f32_dpp v3, v3, v56 quad_perm:[1,0,3,2] row_mask:0xf bank_mask:0xf bound_ctrl:1
	s_nop 0
	v_add_f32_dpp v4, v4, v5 quad_perm:[1,0,3,2] row_mask:0xf bank_mask:0xf bound_ctrl:1
	v_pk_mul_f32 v[144:145], v[128:129], v[48:49]
	v_cndmask_b32_e64 v5, v4, v3, s[98:99]
	v_cndmask_b32_e64 v3, v3, v4, s[98:99]
	v_pk_fma_f32 v[144:145], v[130:131], v[50:51], v[144:145]
	s_nop 0
	v_add_f32_dpp v3, v3, v5 quad_perm:[2,3,0,1] row_mask:0xf bank_mask:0xf bound_ctrl:1
	v_add_f32_e32 v39, v144, v145
	s_nop 0
	v_add_f32_dpp v3, v3, v3 row_ror:4 row_mask:0xf bank_mask:0xf bound_ctrl:1
	s_nop 1
	v_add_f32_dpp v3, v3, v3 row_ror:8 row_mask:0xf bank_mask:0xf bound_ctrl:1
	v_add_f32_e32 v3, v199, v3
	v_min_f32_e32 v3, 0x42a00000, v3
	v_exp_f32_e32 v3, v3
	s_nop 0
	v_add_f32_e32 v4, 1.0, v3
	v_rcp_f32_e32 v4, v4
	s_nop 0
	v_mul_f32_e32 v3, v3, v4
	v_mul_f32_e32 v3, v214, v3
	s_nop 1
	v_mov_b32_dpp v56, v3 quad_perm:[0,0,0,0] row_mask:0xf bank_mask:0xf bound_ctrl:1
	v_mov_b32_dpp v58, v3 quad_perm:[2,2,2,2] row_mask:0xf bank_mask:0xf bound_ctrl:1
	v_mov_b32_dpp v60, v3 quad_perm:[1,1,1,1] row_mask:0xf bank_mask:0xf bound_ctrl:1
	v_mov_b32_dpp v62, v3 quad_perm:[3,3,3,3] row_mask:0xf bank_mask:0xf bound_ctrl:1
	s_waitcnt vmcnt(2)
	v_pk_fma_f32 v[64:65], v[136:137], v[56:57], v[152:153] op_sel_hi:[1,0,1]
	v_pk_fma_f32 v[56:57], v[138:139], v[56:57], v[154:155] op_sel_hi:[1,0,1]
	v_pk_fma_f32 v[66:67], v[136:137], v[58:59], v[156:157] op_sel_hi:[1,0,1]
	v_pk_fma_f32 v[58:59], v[138:139], v[58:59], v[158:159] op_sel_hi:[1,0,1]
	v_pk_fma_f32 v[68:69], v[136:137], v[60:61], v[160:161] op_sel_hi:[1,0,1]
	v_pk_fma_f32 v[60:61], v[138:139], v[60:61], v[162:163] op_sel_hi:[1,0,1]
	v_pk_fma_f32 v[70:71], v[136:137], v[62:63], v[164:165] op_sel_hi:[1,0,1]
	v_pk_fma_f32 v[62:63], v[138:139], v[62:63], v[166:167] op_sel_hi:[1,0,1]
	v_pk_mul_f32 v[136:137], v[128:129], v[40:41]
	v_pk_mul_f32 v[138:139], v[128:129], v[44:45]
	v_pk_mul_f32 v[128:129], v[128:129], v[52:53]
	v_pk_fma_f32 v[136:137], v[130:131], v[42:43], v[136:137]
	v_pk_fma_f32 v[138:139], v[130:131], v[46:47], v[138:139]
	v_pk_fma_f32 v[128:129], v[130:131], v[54:55], v[128:129]
	v_add_f32_e32 v3, v136, v137
	v_add_f32_e32 v5, v138, v139
	v_add_f32_e32 v128, v128, v129
	v_cndmask_b32_e64 v129, v39, v3, s[4:5]
	v_cndmask_b32_e64 v3, v3, v39, s[4:5]
	v_cndmask_b32_e64 v39, v128, v5, s[4:5]
	v_cndmask_b32_e64 v5, v5, v128, s[4:5]
	v_add_f32_dpp v3, v3, v129 quad_perm:[1,0,3,2] row_mask:0xf bank_mask:0xf bound_ctrl:1
	s_nop 0
	v_add_f32_dpp v5, v5, v39 quad_perm:[1,0,3,2] row_mask:0xf bank_mask:0xf bound_ctrl:1
	v_cndmask_b32_e64 v39, v5, v3, s[98:99]
	v_cndmask_b32_e64 v3, v3, v5, s[98:99]
	s_nop 1
	v_add_f32_dpp v3, v3, v39 quad_perm:[2,3,0,1] row_mask:0xf bank_mask:0xf bound_ctrl:1
	s_nop 1
	v_add_f32_dpp v3, v3, v3 row_ror:4 row_mask:0xf bank_mask:0xf bound_ctrl:1
	s_nop 1
	v_add_f32_dpp v3, v3, v3 row_ror:8 row_mask:0xf bank_mask:0xf bound_ctrl:1
	v_add_f32_e32 v3, v199, v3
	v_min_f32_e32 v3, 0x42a00000, v3
	v_exp_f32_e32 v215, v3
	s_nop 0
	v_add_f32_e32 v3, 1.0, v215
	v_rcp_f32_e32 v5, v3
	s_nop 0
	v_pk_mul_f32 v[128:129], v[214:215], v[4:5]
	s_nop 0
	v_pk_mul_f32 v[130:131], v[128:129], v[128:129] op_sel:[0,1] op_sel_hi:[1,0]
	s_nop 1
	v_mov_b32_dpp v4, v130 quad_perm:[0,0,0,0] row_mask:0xf bank_mask:0xf bound_ctrl:1
	v_mov_b32_dpp v136, v130 quad_perm:[2,2,2,2] row_mask:0xf bank_mask:0xf bound_ctrl:1
	v_mov_b32_dpp v138, v130 quad_perm:[1,1,1,1] row_mask:0xf bank_mask:0xf bound_ctrl:1
	v_mov_b32_dpp v130, v130 quad_perm:[3,3,3,3] row_mask:0xf bank_mask:0xf bound_ctrl:1
	v_pk_fma_f32 v[56:57], v[122:123], v[4:5], v[56:57] op_sel_hi:[1,0,1]
	v_pk_fma_f32 v[64:65], v[120:121], v[4:5], v[64:65] op_sel_hi:[1,0,1]
	v_pk_fma_f32 v[58:59], v[122:123], v[136:137], v[58:59] op_sel_hi:[1,0,1]
	v_pk_fma_f32 v[66:67], v[120:121], v[136:137], v[66:67] op_sel_hi:[1,0,1]
	v_pk_fma_f32 v[60:61], v[122:123], v[138:139], v[60:61] op_sel_hi:[1,0,1]
; DI float fexp2(float x) { return __builtin_amdgcn_exp2f(x); }
; DI float frcp(float x) { return __builtin_amdgcn_rcpf(x); }
; template <int CTRL> DI float dppf(float x) { return __builtin_bit_cast(float, __builtin_amdgcn_mov_dpp(__builtin_bit_cast(int, x), CTRL, 0xf, 0xf, true)); }
; DI void smp_key(SmpAcc& A, const f32x4 (&q)[4], const f32x4 K4, const f32x4 V4, float bias2, int c, bool masked) {
;     const f32x2 Kl = __builtin_shufflevector(K4, K4, 0, 1), Kh = __builtin_shufflevector(K4, K4, 2, 3);
;     f32x2 t0 = Kl * __builtin_shufflevector(q[0], q[0], 0, 1), t1 = Kl * __builtin_shufflevector(q[1], q[1], 0, 1), t2 = Kl * __builtin_shufflevector(q[2], q[2], 0, 1), t3 = Kl * __builtin_shufflevector(q[3], q[3], 0, 1);
;     t0 = __builtin_elementwise_fma(Kh, __builtin_shufflevector(q[0], q[0], 2, 3), t0); t1 = __builtin_elementwise_fma(Kh, __builtin_shufflevector(q[1], q[1], 2, 3), t1);
;     t2 = __builtin_elementwise_fma(Kh, __builtin_shufflevector(q[2], q[2], 2, 3), t2); t3 = __builtin_elementwise_fma(Kh, __builtin_shufflevector(q[3], q[3], 2, 3), t3);
;     const float z0 = t0.x + t0.y, z1 = t1.x + t1.y, z2 = t2.x + t2.y, z3 = t3.x + t3.y;
;     const bool b0 = c & 1, b1 = c & 2;
;     const float y0 = (b0 ? z2 : z0) + dppf<0xB1>(b0 ? z0 : z2), y1 = (b0 ? z3 : z1) + dppf<0xB1>(b0 ? z1 : z3);
;     float x = (b1 ? y1 : y0) + dppf<0x4E>(b1 ? y0 : y1);
;     x += dppf<0x124>(x); x += dppf<0x128>(x);
;     const float zz = fminf(x + bias2, 80.f), e = fexp2(zz); float kp = frcp(1.0f + e), sg = e * kp;
;     if (masked) { kp = 1.f; sg = 0.f; }
;     const float w = sg * A.carry;
;     A.carry *= kp;
;     const float w0 = dppf<0x00>(w), w1 = dppf<0xAA>(w), w2 = dppf<0x55>(w), w3 = dppf<0xFF>(w);
;     A.acc[0] += V4 * w0; A.acc[1] += V4 * w1; A.acc[2] += V4 * w2; A.acc[3] += V4 * w3;
	v_pk_fma_f32 v[68:69], v[120:121], v[138:139], v[68:69] op_sel_hi:[1,0,1]
	v_pk_fma_f32 v[62:63], v[122:123], v[130:131], v[62:63] op_sel_hi:[1,0,1]
	v_pk_fma_f32 v[70:71], v[120:121], v[130:131], v[70:71] op_sel_hi:[1,0,1]
	v_pk_mul_f32 v[120:121], v[112:113], v[40:41]
	v_pk_mul_f32 v[122:123], v[112:113], v[44:45]
	v_pk_mul_f32 v[130:131], v[112:113], v[48:49]
	v_pk_mul_f32 v[112:113], v[112:113], v[52:53]
	v_pk_fma_f32 v[120:121], v[114:115], v[42:43], v[120:121]
	v_pk_fma_f32 v[122:123], v[114:115], v[46:47], v[122:123]
	v_pk_fma_f32 v[130:131], v[114:115], v[50:51], v[130:131]
	v_pk_fma_f32 v[112:113], v[114:115], v[54:55], v[112:113]
	v_add_f32_e32 v3, v120, v121
	v_add_f32_e32 v4, v122, v123
	v_add_f32_e32 v39, v130, v131
	v_add_f32_e32 v112, v112, v113
	v_cndmask_b32_e64 v113, v39, v3, s[4:5]
	v_cndmask_b32_e64 v3, v3, v39, s[4:5]
	v_cndmask_b32_e64 v39, v112, v4, s[4:5]
	v_cndmask_b32_e64 v4, v4, v112, s[4:5]
	v_add_f32_dpp v3, v3, v113 quad_perm:[1,0,3,2] row_mask:0xf bank_mask:0xf bound_ctrl:1
	v_mov_b32_e32 v112, v5
	v_add_f32_dpp v4, v4, v39 quad_perm:[1,0,3,2] row_mask:0xf bank_mask:0xf bound_ctrl:1
	v_cndmask_b32_e64 v39, v4, v3, s[98:99]
	v_cndmask_b32_e64 v3, v3, v4, s[98:99]
	v_pk_mul_f32 v[40:41], v[88:89], v[40:41]
	v_pk_mul_f32 v[44:45], v[88:89], v[44:45]
	v_add_f32_dpp v3, v3, v39 quad_perm:[2,3,0,1] row_mask:0xf bank_mask:0xf bound_ctrl:1
	v_pk_mul_f32 v[48:49], v[88:89], v[48:49]
	v_pk_mul_f32 v[52:53], v[88:89], v[52:53]
	v_add_f32_dpp v3, v3, v3 row_ror:4 row_mask:0xf bank_mask:0xf bound_ctrl:1
	v_pk_fma_f32 v[40:41], v[90:91], v[42:43], v[40:41]
	v_pk_fma_f32 v[42:43], v[90:91], v[46:47], v[44:45]
	v_add_f32_dpp v3, v3, v3 row_ror:8 row_mask:0xf bank_mask:0xf bound_ctrl:1
	v_add_f32_e32 v3, v199, v3
	v_min_f32_e32 v3, 0x42a00000, v3
	v_exp_f32_e32 v129, v3
	v_pk_fma_f32 v[44:45], v[90:91], v[50:51], v[48:49]
	v_pk_fma_f32 v[46:47], v[90:91], v[54:55], v[52:53]
	v_add_f32_e32 v39, v44, v45
	v_add_f32_e32 v3, 1.0, v129
	v_rcp_f32_e32 v113, v3
	v_add_f32_e32 v3, v40, v41
	v_add_f32_e32 v40, v46, v47
	v_cndmask_b32_e64 v41, v39, v3, s[4:5]
	v_pk_mul_f32 v[4:5], v[128:129], v[112:113]
	v_cndmask_b32_e64 v3, v3, v39, s[4:5]
	v_pk_mul_f32 v[114:115], v[4:5], v[4:5] op_sel:[0,1] op_sel_hi:[1,0]
	v_add_f32_e32 v5, v42, v43
	v_cndmask_b32_e64 v39, v40, v5, s[4:5]
	v_cndmask_b32_e64 v5, v5, v40, s[4:5]
	v_add_f32_dpp v3, v3, v41 quad_perm:[1,0,3,2] row_mask:0xf bank_mask:0xf bound_ctrl:1
	v_mov_b32_e32 v40, v113
	v_add_f32_dpp v5, v5, v39 quad_perm:[1,0,3,2] row_mask:0xf bank_mask:0xf bound_ctrl:1
	v_cndmask_b32_e64 v39, v5, v3, s[98:99]
	v_cndmask_b32_e64 v3, v3, v5, s[98:99]
	v_mov_b32_dpp v112, v114 quad_perm:[0,0,0,0] row_mask:0xf bank_mask:0xf bound_ctrl:1
	v_mov_b32_dpp v120, v114 quad_perm:[2,2,2,2] row_mask:0xf bank_mask:0xf bound_ctrl:1
	v_add_f32_dpp v3, v3, v39 quad_perm:[2,3,0,1] row_mask:0xf bank_mask:0xf bound_ctrl:1
	v_mov_b32_dpp v122, v114 quad_perm:[1,1,1,1] row_mask:0xf bank_mask:0xf bound_ctrl:1
	v_mov_b32_dpp v114, v114 quad_perm:[3,3,3,3] row_mask:0xf bank_mask:0xf bound_ctrl:1
	v_add_f32_dpp v3, v3, v3 row_ror:4 row_mask:0xf bank_mask:0xf bound_ctrl:1
	v_pk_fma_f32 v[64:65], v[104:105], v[112:113], v[64:65] op_sel_hi:[1,0,1]
	v_pk_fma_f32 v[56:57], v[106:107], v[112:113], v[56:57] op_sel_hi:[1,0,1]
	v_add_f32_dpp v3, v3, v3 row_ror:8 row_mask:0xf bank_mask:0xf bound_ctrl:1
	v_add_f32_e32 v3, v199, v3
	v_min_f32_e32 v3, 0x42a00000, v3
	v_exp_f32_e32 v5, v3
	v_pk_fma_f32 v[66:67], v[104:105], v[120:121], v[66:67] op_sel_hi:[1,0,1]
	v_pk_fma_f32 v[58:59], v[106:107], v[120:121], v[58:59] op_sel_hi:[1,0,1]
	v_pk_fma_f32 v[68:69], v[104:105], v[122:123], v[68:69] op_sel_hi:[1,0,1]
	v_add_f32_e32 v3, 1.0, v5
	v_rcp_f32_e32 v41, v3
	v_pk_fma_f32 v[60:61], v[106:107], v[122:123], v[60:61] op_sel_hi:[1,0,1]
	v_pk_fma_f32 v[70:71], v[104:105], v[114:115], v[70:71] op_sel_hi:[1,0,1]
	v_pk_fma_f32 v[62:63], v[106:107], v[114:115], v[62:63] op_sel_hi:[1,0,1]
	v_pk_mul_f32 v[4:5], v[4:5], v[40:41]
	s_nop 0
	v_pk_mul_f32 v[42:43], v[4:5], v[4:5] op_sel:[0,1] op_sel_hi:[1,0]
	v_mul_f32_e32 v214, v4, v41
	s_nop 0
	v_mov_b32_dpp v4, v42 quad_perm:[0,0,0,0] row_mask:0xf bank_mask:0xf bound_ctrl:1
	v_mov_b32_dpp v40, v42 quad_perm:[2,2,2,2] row_mask:0xf bank_mask:0xf bound_ctrl:1
	v_mov_b32_dpp v44, v42 quad_perm:[1,1,1,1] row_mask:0xf bank_mask:0xf bound_ctrl:1
	v_mov_b32_dpp v42, v42 quad_perm:[3,3,3,3] row_mask:0xf bank_mask:0xf bound_ctrl:1
	v_pk_fma_f32 v[154:155], v[94:95], v[4:5], v[56:57] op_sel_hi:[1,0,1]
	v_pk_fma_f32 v[152:153], v[92:93], v[4:5], v[64:65] op_sel_hi:[1,0,1]
	v_pk_fma_f32 v[158:159], v[94:95], v[40:41], v[58:59] op_sel_hi:[1,0,1]
	v_pk_fma_f32 v[156:157], v[92:93], v[40:41], v[66:67] op_sel_hi:[1,0,1]
	v_pk_fma_f32 v[162:163], v[94:95], v[44:45], v[60:61] op_sel_hi:[1,0,1]
	v_pk_fma_f32 v[160:161], v[92:93], v[44:45], v[68:69] op_sel_hi:[1,0,1]
	v_pk_fma_f32 v[166:167], v[94:95], v[42:43], v[62:63] op_sel_hi:[1,0,1]
	v_pk_fma_f32 v[164:165], v[92:93], v[42:43], v[70:71] op_sel_hi:[1,0,1]

; DI float fexp2(float x) { return __builtin_amdgcn_exp2f(x); }
; DI float frcp(float x) { return __builtin_amdgcn_rcpf(x); }
; template <int CTRL> DI float dppf(float x) { return __builtin_bit_cast(float, __builtin_amdgcn_mov_dpp(__builtin_bit_cast(int, x), CTRL, 0xf, 0xf, true)); }
; DI void smp_key(SmpAcc& A, const f32x4 (&q)[4], const f32x4 K4, const f32x4 V4, float bias2, int c, bool masked) {
;     const f32x2 Kl = __builtin_shufflevector(K4, K4, 0, 1), Kh = __builtin_shufflevector(K4, K4, 2, 3);
;     f32x2 t0 = Kl * __builtin_shufflevector(q[0], q[0], 0, 1), t1 = Kl * __builtin_shufflevector(q[1], q[1], 0, 1), t2 = Kl * __builtin_shufflevector(q[2], q[2], 0, 1), t3 = Kl * __builtin_shufflevector(q[3], q[3], 0, 1);
;     t0 = __builtin_elementwise_fma(Kh, __builtin_shufflevector(q[0], q[0], 2, 3), t0); t1 = __builtin_elementwise_fma(Kh, __builtin_shufflevector(q[1], q[1], 2, 3), t1);
;     t2 = __builtin_elementwise_fma(Kh, __builtin_shufflevector(q[2], q[2], 2, 3), t2); t3 = __builtin_elementwise_fma(Kh, __builtin_shufflevector(q[3], q[3], 2, 3), t3);
;     const float z0 = t0.x + t0.y, z1 = t1.x + t1.y, z2 = t2.x + t2.y, z3 = t3.x + t3.y;
;     const bool b0 = c & 1, b1 = c & 2;
;     const float y0 = (b0 ? z2 : z0) + dppf<0xB1>(b0 ? z0 : z2), y1 = (b0 ? z3 : z1) + dppf<0xB1>(b0 ? z1 : z3);
;     float x = (b1 ? y1 : y0) + dppf<0x4E>(b1 ? y0 : y1);
;     x += dppf<0x124>(x); x += dppf<0x128>(x);
;     const float zz = fminf(x + bias2, 80.f), e = fexp2(zz); float kp = frcp(1.0f + e), sg = e * kp;
;     if (masked) { kp = 1.f; sg = 0.f; }
;     const float w = sg * A.carry;
;     A.carry *= kp;
;     const float w0 = dppf<0x00>(w), w1 = dppf<0xAA>(w), w2 = dppf<0x55>(w), w3 = dppf<0xFF>(w);
;     A.acc[0] += V4 * w0; A.acc[1] += V4 * w1; A.acc[2] += V4 * w2; A.acc[3] += V4 * w3;
.LBB0_641:
	ds_read_b128 v[40:43], v197
	ds_read_b128 v[44:47], v197 offset:1024
	ds_read_b128 v[48:51], v197 offset:2048
	ds_read_b128 v[52:55], v197 offset:3072
	s_waitcnt vmcnt(12) lgkmcnt(3)
	v_pk_mul_f32 v[4:5], v[148:149], v[40:41]
	s_waitcnt lgkmcnt(2)
	v_pk_mul_f32 v[56:57], v[148:149], v[44:45]
	s_waitcnt lgkmcnt(1)
	v_pk_mul_f32 v[58:59], v[148:149], v[48:49]
	s_waitcnt lgkmcnt(0)
	v_pk_mul_f32 v[60:61], v[148:149], v[52:53]
	v_pk_fma_f32 v[4:5], v[150:151], v[42:43], v[4:5]
	v_pk_fma_f32 v[56:57], v[150:151], v[46:47], v[56:57]
	v_pk_fma_f32 v[58:59], v[150:151], v[50:51], v[58:59]
	v_pk_fma_f32 v[60:61], v[150:151], v[54:55], v[60:61]
	v_add_f32_e32 v3, v4, v5
	v_add_f32_e32 v4, v56, v57
	v_add_f32_e32 v5, v58, v59
	v_add_f32_e32 v39, v60, v61
	v_cndmask_b32_e64 v56, v5, v3, s[4:5]
	v_cndmask_b32_e64 v3, v3, v5, s[4:5]
	v_cndmask_b32_e64 v5, v39, v4, s[4:5]
	v_cndmask_b32_e64 v4, v4, v39, s[4:5]
	v_add_f32_dpp v3, v3, v56 quad_perm:[1,0,3,2] row_mask:0xf bank_mask:0xf bound_ctrl:1
	s_nop 0
	v_add_f32_dpp v4, v4, v5 quad_perm:[1,0,3,2] row_mask:0xf bank_mask:0xf bound_ctrl:1
	v_pk_mul_f32 v[148:149], v[132:133], v[48:49]
	v_cndmask_b32_e64 v5, v4, v3, s[98:99]
	v_cndmask_b32_e64 v3, v3, v4, s[98:99]
	v_pk_fma_f32 v[148:149], v[134:135], v[50:51], v[148:149]
	s_nop 0
	v_add_f32_dpp v3, v3, v5 quad_perm:[2,3,0,1] row_mask:0xf bank_mask:0xf bound_ctrl:1
	v_add_f32_e32 v39, v148, v149
	s_nop 0
	v_add_f32_dpp v3, v3, v3 row_ror:4 row_mask:0xf bank_mask:0xf bound_ctrl:1
	s_nop 1
	v_add_f32_dpp v3, v3, v3 row_ror:8 row_mask:0xf bank_mask:0xf bound_ctrl:1
	v_add_f32_e32 v3, v199, v3
	v_min_f32_e32 v3, 0x42a00000, v3
	v_exp_f32_e32 v3, v3
	s_nop 0
	v_add_f32_e32 v4, 1.0, v3
	v_rcp_f32_e32 v4, v4
	s_nop 0
	v_mul_f32_e32 v3, v3, v4
	v_mul_f32_e32 v3, v214, v3
	s_nop 1
	v_mov_b32_dpp v56, v3 quad_perm:[0,0,0,0] row_mask:0xf bank_mask:0xf bound_ctrl:1
	v_mov_b32_dpp v58, v3 quad_perm:[2,2,2,2] row_mask:0xf bank_mask:0xf bound_ctrl:1
	v_mov_b32_dpp v60, v3 quad_perm:[1,1,1,1] row_mask:0xf bank_mask:0xf bound_ctrl:1
	v_mov_b32_dpp v62, v3 quad_perm:[3,3,3,3] row_mask:0xf bank_mask:0xf bound_ctrl:1
	s_waitcnt vmcnt(10)
	v_pk_fma_f32 v[64:65], v[140:141], v[56:57], v[152:153] op_sel_hi:[1,0,1]
	v_pk_fma_f32 v[56:57], v[142:143], v[56:57], v[154:155] op_sel_hi:[1,0,1]
	v_pk_fma_f32 v[66:67], v[140:141], v[58:59], v[156:157] op_sel_hi:[1,0,1]
	v_pk_fma_f32 v[58:59], v[142:143], v[58:59], v[158:159] op_sel_hi:[1,0,1]
	v_pk_fma_f32 v[68:69], v[140:141], v[60:61], v[160:161] op_sel_hi:[1,0,1]
	v_pk_fma_f32 v[60:61], v[142:143], v[60:61], v[162:163] op_sel_hi:[1,0,1]
	v_pk_fma_f32 v[70:71], v[140:141], v[62:63], v[164:165] op_sel_hi:[1,0,1]
	v_pk_fma_f32 v[62:63], v[142:143], v[62:63], v[166:167] op_sel_hi:[1,0,1]
	v_pk_mul_f32 v[140:141], v[132:133], v[40:41]
	v_pk_mul_f32 v[142:143], v[132:133], v[44:45]
	v_pk_mul_f32 v[132:133], v[132:133], v[52:53]
	v_pk_fma_f32 v[140:141], v[134:135], v[42:43], v[140:141]
	v_pk_fma_f32 v[142:143], v[134:135], v[46:47], v[142:143]
	v_pk_fma_f32 v[132:133], v[134:135], v[54:55], v[132:133]
	v_add_f32_e32 v3, v140, v141
	v_add_f32_e32 v5, v142, v143
	v_add_f32_e32 v132, v132, v133
	v_cndmask_b32_e64 v133, v39, v3, s[4:5]
	v_cndmask_b32_e64 v3, v3, v39, s[4:5]
	v_cndmask_b32_e64 v39, v132, v5, s[4:5]
	v_cndmask_b32_e64 v5, v5, v132, s[4:5]
	v_add_f32_dpp v3, v3, v133 quad_perm:[1,0,3,2] row_mask:0xf bank_mask:0xf bound_ctrl:1
	s_nop 0
	v_add_f32_dpp v5, v5, v39 quad_perm:[1,0,3,2] row_mask:0xf bank_mask:0xf bound_ctrl:1
	v_cndmask_b32_e64 v39, v5, v3, s[98:99]
	v_cndmask_b32_e64 v3, v3, v5, s[98:99]
	s_nop 1
	v_add_f32_dpp v3, v3, v39 quad_perm:[2,3,0,1] row_mask:0xf bank_mask:0xf bound_ctrl:1
	s_nop 1
	v_add_f32_dpp v3, v3, v3 row_ror:4 row_mask:0xf bank_mask:0xf bound_ctrl:1
	s_nop 1
	v_add_f32_dpp v3, v3, v3 row_ror:8 row_mask:0xf bank_mask:0xf bound_ctrl:1
	v_add_f32_e32 v3, v199, v3
	v_min_f32_e32 v3, 0x42a00000, v3
	v_exp_f32_e32 v215, v3
	s_nop 0
	v_add_f32_e32 v3, 1.0, v215
	v_rcp_f32_e32 v5, v3
	s_nop 0
	v_pk_mul_f32 v[132:133], v[214:215], v[4:5]
	s_nop 0
	v_pk_mul_f32 v[134:135], v[132:133], v[132:133] op_sel:[0,1] op_sel_hi:[1,0]
	s_nop 1
	v_mov_b32_dpp v4, v134 quad_perm:[0,0,0,0] row_mask:0xf bank_mask:0xf bound_ctrl:1
	v_mov_b32_dpp v140, v134 quad_perm:[2,2,2,2] row_mask:0xf bank_mask:0xf bound_ctrl:1
	v_mov_b32_dpp v142, v134 quad_perm:[1,1,1,1] row_mask:0xf bank_mask:0xf bound_ctrl:1
	v_mov_b32_dpp v134, v134 quad_perm:[3,3,3,3] row_mask:0xf bank_mask:0xf bound_ctrl:1
	v_pk_fma_f32 v[56:57], v[126:127], v[4:5], v[56:57] op_sel_hi:[1,0,1]
	v_pk_fma_f32 v[64:65], v[124:125], v[4:5], v[64:65] op_sel_hi:[1,0,1]
	v_pk_fma_f32 v[58:59], v[126:127], v[140:141], v[58:59] op_sel_hi:[1,0,1]
	v_pk_fma_f32 v[66:67], v[124:125], v[140:141], v[66:67] op_sel_hi:[1,0,1]
	v_pk_fma_f32 v[60:61], v[126:127], v[142:143], v[60:61] op_sel_hi:[1,0,1]
	v_pk_fma_f32 v[68:69], v[124:125], v[142:143], v[68:69] op_sel_hi:[1,0,1]
; DI float fexp2(float x) { return __builtin_amdgcn_exp2f(x); }
; DI float frcp(float x) { return __builtin_amdgcn_rcpf(x); }
; template <int CTRL> DI float dppf(float x) { return __builtin_bit_cast(float, __builtin_amdgcn_mov_dpp(__builtin_bit_cast(int, x), CTRL, 0xf, 0xf, true)); }
; DI void smp_key(SmpAcc& A, const f32x4 (&q)[4], const f32x4 K4, const f32x4 V4, float bias2, int c, bool masked) {
;     const f32x2 Kl = __builtin_shufflevector(K4, K4, 0, 1), Kh = __builtin_shufflevector(K4, K4, 2, 3);
;     f32x2 t0 = Kl * __builtin_shufflevector(q[0], q[0], 0, 1), t1 = Kl * __builtin_shufflevector(q[1], q[1], 0, 1), t2 = Kl * __builtin_shufflevector(q[2], q[2], 0, 1), t3 = Kl * __builtin_shufflevector(q[3], q[3], 0, 1);
;     t0 = __builtin_elementwise_fma(Kh, __builtin_shufflevector(q[0], q[0], 2, 3), t0); t1 = __builtin_elementwise_fma(Kh, __builtin_shufflevector(q[1], q[1], 2, 3), t1);
;     t2 = __builtin_elementwise_fma(Kh, __builtin_shufflevector(q[2], q[2], 2, 3), t2); t3 = __builtin_elementwise_fma(Kh, __builtin_shufflevector(q[3], q[3], 2, 3), t3);
;     const float z0 = t0.x + t0.y, z1 = t1.x + t1.y, z2 = t2.x + t2.y, z3 = t3.x + t3.y;
;     const bool b0 = c & 1, b1 = c & 2;
;     const float y0 = (b0 ? z2 : z0) + dppf<0xB1>(b0 ? z0 : z2), y1 = (b0 ? z3 : z1) + dppf<0xB1>(b0 ? z1 : z3);
;     float x = (b1 ? y1 : y0) + dppf<0x4E>(b1 ? y0 : y1);
;     x += dppf<0x124>(x); x += dppf<0x128>(x);
;     const float zz = fminf(x + bias2, 80.f), e = fexp2(zz); float kp = frcp(1.0f + e), sg = e * kp;
;     if (masked) { kp = 1.f; sg = 0.f; }
;     const float w = sg * A.carry;
;     A.carry *= kp;
;     const float w0 = dppf<0x00>(w), w1 = dppf<0xAA>(w), w2 = dppf<0x55>(w), w3 = dppf<0xFF>(w);
;     A.acc[0] += V4 * w0; A.acc[1] += V4 * w1; A.acc[2] += V4 * w2; A.acc[3] += V4 * w3;
	v_pk_fma_f32 v[62:63], v[126:127], v[134:135], v[62:63] op_sel_hi:[1,0,1]
	v_pk_fma_f32 v[70:71], v[124:125], v[134:135], v[70:71] op_sel_hi:[1,0,1]
	v_pk_mul_f32 v[124:125], v[116:117], v[40:41]
	v_pk_mul_f32 v[126:127], v[116:117], v[44:45]
	v_pk_mul_f32 v[134:135], v[116:117], v[48:49]
	v_pk_mul_f32 v[116:117], v[116:117], v[52:53]
	v_pk_fma_f32 v[124:125], v[118:119], v[42:43], v[124:125]
	v_pk_fma_f32 v[126:127], v[118:119], v[46:47], v[126:127]
	v_pk_fma_f32 v[134:135], v[118:119], v[50:51], v[134:135]
	v_pk_fma_f32 v[116:117], v[118:119], v[54:55], v[116:117]
	v_add_f32_e32 v3, v124, v125
	v_add_f32_e32 v4, v126, v127
	v_add_f32_e32 v39, v134, v135
	v_add_f32_e32 v116, v116, v117
	v_cndmask_b32_e64 v117, v39, v3, s[4:5]
	v_cndmask_b32_e64 v3, v3, v39, s[4:5]
	v_cndmask_b32_e64 v39, v116, v4, s[4:5]
	v_cndmask_b32_e64 v4, v4, v116, s[4:5]
	v_add_f32_dpp v3, v3, v117 quad_perm:[1,0,3,2] row_mask:0xf bank_mask:0xf bound_ctrl:1
	v_mov_b32_e32 v116, v5
	v_add_f32_dpp v4, v4, v39 quad_perm:[1,0,3,2] row_mask:0xf bank_mask:0xf bound_ctrl:1
	v_cndmask_b32_e64 v39, v4, v3, s[98:99]
	v_cndmask_b32_e64 v3, v3, v4, s[98:99]
	v_pk_mul_f32 v[40:41], v[100:101], v[40:41]
	v_pk_mul_f32 v[44:45], v[100:101], v[44:45]
	v_add_f32_dpp v3, v3, v39 quad_perm:[2,3,0,1] row_mask:0xf bank_mask:0xf bound_ctrl:1
	v_pk_mul_f32 v[48:49], v[100:101], v[48:49]
	v_pk_mul_f32 v[52:53], v[100:101], v[52:53]
	v_add_f32_dpp v3, v3, v3 row_ror:4 row_mask:0xf bank_mask:0xf bound_ctrl:1
	v_pk_fma_f32 v[40:41], v[102:103], v[42:43], v[40:41]
	v_pk_fma_f32 v[42:43], v[102:103], v[46:47], v[44:45]
	v_add_f32_dpp v3, v3, v3 row_ror:8 row_mask:0xf bank_mask:0xf bound_ctrl:1
	v_add_f32_e32 v3, v199, v3
	v_min_f32_e32 v3, 0x42a00000, v3
	v_exp_f32_e32 v133, v3
	v_pk_fma_f32 v[44:45], v[102:103], v[50:51], v[48:49]
	v_pk_fma_f32 v[46:47], v[102:103], v[54:55], v[52:53]
	v_add_f32_e32 v39, v44, v45
	v_add_f32_e32 v3, 1.0, v133
	v_rcp_f32_e32 v117, v3
	v_add_f32_e32 v3, v40, v41
	v_add_f32_e32 v40, v46, v47
	v_cndmask_b32_e64 v41, v39, v3, s[4:5]
	v_pk_mul_f32 v[4:5], v[132:133], v[116:117]
	v_cndmask_b32_e64 v3, v3, v39, s[4:5]
	v_pk_mul_f32 v[118:119], v[4:5], v[4:5] op_sel:[0,1] op_sel_hi:[1,0]
	v_add_f32_e32 v5, v42, v43
	v_cndmask_b32_e64 v39, v40, v5, s[4:5]
	v_cndmask_b32_e64 v5, v5, v40, s[4:5]
	v_add_f32_dpp v3, v3, v41 quad_perm:[1,0,3,2] row_mask:0xf bank_mask:0xf bound_ctrl:1
	v_mov_b32_e32 v40, v117
	v_add_f32_dpp v5, v5, v39 quad_perm:[1,0,3,2] row_mask:0xf bank_mask:0xf bound_ctrl:1
	v_cndmask_b32_e64 v39, v5, v3, s[98:99]
	v_cndmask_b32_e64 v3, v3, v5, s[98:99]
	v_mov_b32_dpp v116, v118 quad_perm:[0,0,0,0] row_mask:0xf bank_mask:0xf bound_ctrl:1
	v_mov_b32_dpp v124, v118 quad_perm:[2,2,2,2] row_mask:0xf bank_mask:0xf bound_ctrl:1
	v_add_f32_dpp v3, v3, v39 quad_perm:[2,3,0,1] row_mask:0xf bank_mask:0xf bound_ctrl:1
	v_mov_b32_dpp v126, v118 quad_perm:[1,1,1,1] row_mask:0xf bank_mask:0xf bound_ctrl:1
	v_mov_b32_dpp v118, v118 quad_perm:[3,3,3,3] row_mask:0xf bank_mask:0xf bound_ctrl:1
	v_add_f32_dpp v3, v3, v3 row_ror:4 row_mask:0xf bank_mask:0xf bound_ctrl:1
	v_pk_fma_f32 v[64:65], v[108:109], v[116:117], v[64:65] op_sel_hi:[1,0,1]
	v_pk_fma_f32 v[56:57], v[110:111], v[116:117], v[56:57] op_sel_hi:[1,0,1]
	v_add_f32_dpp v3, v3, v3 row_ror:8 row_mask:0xf bank_mask:0xf bound_ctrl:1
	v_add_f32_e32 v3, v199, v3
	v_min_f32_e32 v3, 0x42a00000, v3
	v_exp_f32_e32 v5, v3
	v_pk_fma_f32 v[66:67], v[108:109], v[124:125], v[66:67] op_sel_hi:[1,0,1]
	v_pk_fma_f32 v[58:59], v[110:111], v[124:125], v[58:59] op_sel_hi:[1,0,1]
	v_pk_fma_f32 v[68:69], v[108:109], v[126:127], v[68:69] op_sel_hi:[1,0,1]
	v_add_f32_e32 v3, 1.0, v5
	v_rcp_f32_e32 v41, v3
	v_pk_fma_f32 v[60:61], v[110:111], v[126:127], v[60:61] op_sel_hi:[1,0,1]
	v_pk_fma_f32 v[70:71], v[108:109], v[118:119], v[70:71] op_sel_hi:[1,0,1]
	v_pk_fma_f32 v[62:63], v[110:111], v[118:119], v[62:63] op_sel_hi:[1,0,1]
	v_pk_mul_f32 v[4:5], v[4:5], v[40:41]
	s_nop 0
	v_pk_mul_f32 v[42:43], v[4:5], v[4:5] op_sel:[0,1] op_sel_hi:[1,0]
	v_mul_f32_e32 v214, v4, v41
	s_nop 0
	v_mov_b32_dpp v4, v42 quad_perm:[0,0,0,0] row_mask:0xf bank_mask:0xf bound_ctrl:1
	v_mov_b32_dpp v40, v42 quad_perm:[2,2,2,2] row_mask:0xf bank_mask:0xf bound_ctrl:1
	v_mov_b32_dpp v44, v42 quad_perm:[1,1,1,1] row_mask:0xf bank_mask:0xf bound_ctrl:1
	v_mov_b32_dpp v42, v42 quad_perm:[3,3,3,3] row_mask:0xf bank_mask:0xf bound_ctrl:1
	v_pk_fma_f32 v[154:155], v[98:99], v[4:5], v[56:57] op_sel_hi:[1,0,1]
	v_pk_fma_f32 v[152:153], v[96:97], v[4:5], v[64:65] op_sel_hi:[1,0,1]
	v_pk_fma_f32 v[158:159], v[98:99], v[40:41], v[58:59] op_sel_hi:[1,0,1]
	v_pk_fma_f32 v[156:157], v[96:97], v[40:41], v[66:67] op_sel_hi:[1,0,1]
	v_pk_fma_f32 v[162:163], v[98:99], v[44:45], v[60:61] op_sel_hi:[1,0,1]
	v_pk_fma_f32 v[160:161], v[96:97], v[44:45], v[68:69] op_sel_hi:[1,0,1]
	v_pk_fma_f32 v[166:167], v[98:99], v[42:43], v[62:63] op_sel_hi:[1,0,1]
	v_pk_fma_f32 v[164:165], v[96:97], v[42:43], v[70:71] op_sel_hi:[1,0,1]
